# lever 7 instruction selection: rmsnorm loops use v_cvt_pk_bf16_f32 (hardware RNE) for 29 of 48 output pairs instead of the 6-op bfe/add3/lshr/and_or rounding sequence
# speedup vs baseline: 1.0074x; 1.0015x over previous
; __device__ __forceinline__ float wave_sum(float v, int lane) {
; #pragma unroll
;     for (int o = 1; o < 64; o <<= 1) v += __builtin_bit_cast(float, __builtin_amdgcn_ds_bpermute((lane ^ o) << 2, __builtin_bit_cast(int, v)));
;     return v;
; }
; __device__ __forceinline__ void rms_row2(const float* xrow0, const float* xrow1, const float* g, bf16* xo0, bf16* xo1, float* fo0, float* fo1, int lane) {
;     const f32x4* xr0 = (const f32x4*)xrow0 + lane; const f32x4* xr1 = (const f32x4*)xrow1 + lane; const f32x4* gr = (const f32x4*)g + lane;
;     f32x4 v0[4], v1[4]; float s0 = 0.f, s1 = 0.f;
; #pragma unroll
;     for (int j = 0; j < 4; ++j) { v0[j] = xr0[64 * j]; v1[j] = xr1[64 * j]; }
; #pragma unroll
;     for (int j = 0; j < 4; ++j) { s0 += (v0[j].x * v0[j].x + v0[j].y * v0[j].y) + (v0[j].z * v0[j].z + v0[j].w * v0[j].w); s1 += (v1[j].x * v1[j].x + v1[j].y * v1[j].y) + (v1[j].z * v1[j].z + v1[j].w * v1[j].w); }
;     const float r0 = 1.0f / sqrtf(wave_sum(s0, lane) * (1.f / DM) + EPS), r1 = 1.0f / sqrtf(wave_sum(s1, lane) * (1.f / DM) + EPS);
.LBB0_69:
	global_load_dwordx4 v[12:15], v[36:37], off
	global_load_dwordx4 v[8:11], v[36:37], off offset:1024
	global_load_dwordx4 v[0:3], v[36:37], off offset:3072
	global_load_dwordx4 v[4:7], v[36:37], off offset:2048
	s_add_i32 s1, s31, s0
	s_cmp_lt_i32 s1, 0x8000
	s_cselect_b32 s4, s1, s0
	s_ashr_i32 s5, s4, 31
	s_lshl_b64 s[6:7], s[4:5], 12
	v_lshl_add_u64 v[20:21], v[28:29], 0, s[6:7]
	global_load_dwordx4 v[24:27], v[30:31], off
	global_load_dwordx4 v[48:51], v[20:21], off
	global_load_dwordx4 v[52:55], v[20:21], off offset:1024
	global_load_dwordx4 v[16:19], v[20:21], off offset:3072
	s_nop 0
	global_load_dwordx4 v[20:23], v[20:21], off offset:2048
	s_lshl_b64 s[4:5], s[4:5], 11
	v_lshl_add_u64 v[38:39], v[32:33], 0, s[4:5]
	s_add_i32 s0, s0, s12
	v_lshl_add_u64 v[36:37], v[36:37], 0, s[14:15]
	s_cmpk_gt_i32 s0, 0x7fff
	s_waitcnt vmcnt(8)
	v_pk_mul_f32 v[56:57], v[14:15], v[14:15]
	v_pk_mul_f32 v[58:59], v[12:13], v[12:13]
	s_waitcnt vmcnt(7)
	v_pk_mul_f32 v[60:61], v[10:11], v[10:11]
	v_pk_mul_f32 v[62:63], v[8:9], v[8:9]
	v_pk_mov_b32 v[68:69], v[58:59], v[56:57] op_sel:[1,0]
	v_mov_b32_e32 v59, v57
	v_pk_mov_b32 v[56:57], v[62:63], v[60:61] op_sel:[1,0]
	v_mov_b32_e32 v63, v61
	s_waitcnt vmcnt(6)
	v_mul_f32_e32 v67, v1, v1
	s_waitcnt vmcnt(5)
	v_mul_f32_e32 v64, v5, v5
	v_mul_f32_e32 v66, v7, v7
	v_pk_add_f32 v[58:59], v[68:69], v[58:59]
	v_pk_add_f32 v[56:57], v[56:57], v[62:63]
	v_mul_f32_e32 v47, v0, v0
	v_mul_f32_e32 v70, v2, v2
	v_mul_f32_e32 v71, v3, v3
	v_pk_fma_f32 v[60:61], v[4:5], v[4:5], v[64:65] op_sel_hi:[1,1,0]
	v_pk_fma_f32 v[64:65], v[6:7], v[6:7], v[66:67] op_sel_hi:[1,1,0]
	v_pk_add_f32 v[58:59], v[58:59], v[58:59] op_sel:[0,1] op_sel_hi:[1,0]
	v_pk_add_f32 v[56:57], v[56:57], v[56:57] op_sel:[0,1] op_sel_hi:[1,0]
	v_mov_b32_e32 v61, v70
	v_mov_b32_e32 v65, v71
	v_mov_b32_e32 v59, v47
	v_mov_b32_e32 v57, v67
	v_pk_add_f32 v[60:61], v[60:61], v[64:65]
	v_pk_add_f32 v[56:57], v[58:59], v[56:57]
	s_waitcnt vmcnt(3)
	v_pk_mul_f32 v[58:59], v[50:51], v[50:51]
	v_pk_mul_f32 v[62:63], v[48:49], v[48:49]
	s_waitcnt vmcnt(2)
	v_pk_mul_f32 v[64:65], v[54:55], v[54:55]
	v_pk_mul_f32 v[66:67], v[52:53], v[52:53]
	v_pk_add_f32 v[56:57], v[56:57], v[60:61]
	v_pk_mov_b32 v[70:71], v[62:63], v[58:59] op_sel:[1,0]
	v_mov_b32_e32 v63, v59
	v_pk_mov_b32 v[58:59], v[66:67], v[64:65] op_sel:[1,0]
	v_mov_b32_e32 v67, v65
	v_add_f32_e32 v64, v56, v57
	s_waitcnt vmcnt(1)
	v_mul_f32_e32 v69, v17, v17
	s_waitcnt vmcnt(0)
	v_mul_f32_e32 v60, v21, v21
	v_mul_f32_e32 v68, v23, v23
	v_pk_add_f32 v[62:63], v[70:71], v[62:63]
	v_pk_add_f32 v[58:59], v[58:59], v[66:67]
	ds_bpermute_b32 v65, v41, v64
	v_mul_f32_e32 v47, v16, v16
	v_mul_f32_e32 v72, v18, v18
	v_mul_f32_e32 v73, v19, v19
	v_pk_fma_f32 v[56:57], v[20:21], v[20:21], v[60:61] op_sel_hi:[1,1,0]
	v_pk_fma_f32 v[60:61], v[22:23], v[22:23], v[68:69] op_sel_hi:[1,1,0]
	v_pk_add_f32 v[62:63], v[62:63], v[62:63] op_sel:[0,1] op_sel_hi:[1,0]
	v_pk_add_f32 v[58:59], v[58:59], v[58:59] op_sel:[0,1] op_sel_hi:[1,0]
	v_mov_b32_e32 v57, v72
	v_mov_b32_e32 v61, v73
	v_mov_b32_e32 v63, v47
	v_mov_b32_e32 v59, v69
	v_pk_add_f32 v[56:57], v[56:57], v[60:61]
	v_pk_add_f32 v[58:59], v[62:63], v[58:59]
	s_nop 0
	v_pk_add_f32 v[56:57], v[58:59], v[56:57]
	s_nop 0
	v_add_f32_e32 v47, v56, v57
	s_waitcnt lgkmcnt(0)
	v_add_f32_e32 v56, v64, v65
	ds_bpermute_b32 v57, v42, v56
	ds_bpermute_b32 v58, v41, v47
	s_waitcnt lgkmcnt(1)
	v_add_f32_e32 v56, v56, v57
	s_waitcnt lgkmcnt(0)
	v_add_f32_e32 v47, v47, v58
	ds_bpermute_b32 v57, v43, v56
	ds_bpermute_b32 v58, v42, v47
	s_waitcnt lgkmcnt(1)
	v_add_f32_e32 v56, v56, v57
	s_waitcnt lgkmcnt(0)
	v_add_f32_e32 v47, v47, v58
	ds_bpermute_b32 v57, v44, v56
	ds_bpermute_b32 v58, v43, v47
	s_waitcnt lgkmcnt(1)
	v_add_f32_e32 v56, v56, v57
	s_waitcnt lgkmcnt(0)
	v_add_f32_e32 v47, v47, v58
	ds_bpermute_b32 v57, v45, v56
	ds_bpermute_b32 v58, v44, v47
	s_waitcnt lgkmcnt(1)
	v_add_f32_e32 v56, v56, v57
	s_waitcnt lgkmcnt(0)
	v_add_f32_e32 v47, v47, v58
	ds_bpermute_b32 v57, v46, v56
	ds_bpermute_b32 v58, v45, v47
	s_waitcnt lgkmcnt(1)
	v_add_f32_e32 v56, v56, v57
	s_waitcnt lgkmcnt(0)
	v_add_f32_e32 v47, v47, v58
	v_fmamk_f32 v56, v56, 0x3a800000, v240
	ds_bpermute_b32 v57, v46, v47
	v_mul_f32_e32 v58, 0x4f800000, v56
	v_cmp_gt_f32_e32 vcc, s18, v56
	s_waitcnt lgkmcnt(0)
; __device__ __forceinline__ unsigned pk2(float lo, float hi) { return f2bf(lo) | (f2bf(hi) << 16); }
; __device__ __forceinline__ void rms_row2(const float* xrow0, const float* xrow1, const float* g, bf16* xo0, bf16* xo1, float* fo0, float* fo1, int lane) {
;     ...
;     const float r0 = 1.0f / sqrtf(wave_sum(s0, lane) * (1.f / DM) + EPS), r1 = 1.0f / sqrtf(wave_sum(s1, lane) * (1.f / DM) + EPS);
; #pragma unroll
;     for (int j = 0; j < 4; ++j) { const f32x4 gg = gr[64 * j]; const f32x4 y0 = v0[j] * r0 * gg, y1 = v1[j] * r1 * gg;
;         if (xo0) { ((unsigned long long*)xo0)[lane + 64 * j] = (unsigned long long)pk2(y0.x, y0.y) | ((unsigned long long)pk2(y0.z, y0.w) << 32);
;                    ((unsigned long long*)xo1)[lane + 64 * j] = (unsigned long long)pk2(y1.x, y1.y) | ((unsigned long long)pk2(y1.z, y1.w) << 32); }
;         else { ((f32x4*)fo0)[lane + 64 * j] = y0; ((f32x4*)fo1)[lane + 64 * j] = y1; } }
	v_add_f32_e32 v47, v47, v57
	v_cndmask_b32_e32 v56, v56, v58, vcc
	v_sqrt_f32_e32 v58, v56
	v_fmamk_f32 v47, v47, 0x3a800000, v240
	v_mul_f32_e32 v60, 0x4f800000, v47
	v_cmp_gt_f32_e64 s[4:5], s18, v47
	v_add_u32_e32 v57, -1, v58
	v_add_u32_e32 v59, 1, v58
	v_fma_f32 v61, -v57, v58, v56
	v_fma_f32 v62, -v59, v58, v56
	v_cndmask_b32_e64 v47, v47, v60, s[4:5]
	v_cmp_ge_f32_e64 s[6:7], 0, v61
	s_nop 1
	v_cndmask_b32_e64 v57, v58, v57, s[6:7]
	v_sqrt_f32_e32 v58, v47
	v_cmp_lt_f32_e64 s[6:7], 0, v62
	s_nop 1
	v_cndmask_b32_e64 v57, v57, v59, s[6:7]
	v_mul_f32_e32 v59, 0x37800000, v57
	v_cndmask_b32_e32 v57, v57, v59, vcc
	v_cmp_class_f32_e32 vcc, v56, v244
	v_add_u32_e32 v59, 1, v58
	v_fma_f32 v63, -v59, v58, v47
	v_cndmask_b32_e32 v56, v57, v56, vcc
	v_add_u32_e32 v57, -1, v58
	v_div_scale_f32 v60, s[6:7], v56, v56, 1.0
	v_fma_f32 v62, -v57, v58, v47
	v_cmp_ge_f32_e64 s[6:7], 0, v62
	v_rcp_f32_e32 v64, v60
	v_div_scale_f32 v61, vcc, 1.0, v56, 1.0
	v_cndmask_b32_e64 v57, v58, v57, s[6:7]
	v_cmp_lt_f32_e64 s[6:7], 0, v63
	s_nop 1
	v_cndmask_b32_e64 v57, v57, v59, s[6:7]
	v_mul_f32_e32 v58, 0x37800000, v57
	v_cndmask_b32_e64 v57, v57, v58, s[4:5]
	v_cmp_class_f32_e64 s[4:5], v47, v244
	v_fma_f32 v58, -v60, v64, 1.0
	v_fmac_f32_e32 v64, v58, v64
	v_cndmask_b32_e64 v47, v57, v47, s[4:5]
	v_div_scale_f32 v57, s[4:5], v47, v47, 1.0
	v_mul_f32_e32 v59, v61, v64
	v_rcp_f32_e32 v62, v57
	v_fma_f32 v63, -v60, v59, v61
	v_fmac_f32_e32 v59, v63, v64
	v_fma_f32 v60, -v60, v59, v61
	v_div_fmas_f32 v59, v60, v64, v59
	v_fma_f32 v60, -v57, v62, 1.0
	v_div_scale_f32 v58, s[4:5], 1.0, v47, 1.0
	v_fmac_f32_e32 v62, v60, v62
	v_div_fixup_f32 v56, v59, v56, 1.0
	v_mul_f32_e32 v59, v58, v62
	v_pk_mul_f32 v[12:13], v[12:13], v[56:57] op_sel_hi:[1,0]
	v_pk_mul_f32 v[14:15], v[14:15], v[56:57] op_sel_hi:[1,0]
	v_fma_f32 v60, -v57, v59, v58
	v_pk_mul_f32 v[14:15], v[26:27], v[14:15]
	v_pk_mul_f32 v[12:13], v[24:25], v[12:13]
	v_fmac_f32_e32 v59, v60, v62
	v_fma_f32 v57, -v57, v59, v58
	s_mov_b64 vcc, s[4:5]
	v_div_fmas_f32 v57, v57, v62, v59
	v_div_fixup_f32 v58, v57, v47, 1.0
	v_cvt_pk_bf16_f32 v12, v12, v13
	v_cvt_pk_bf16_f32 v13, v14, v15
	v_pk_mul_f32 v[14:15], v[48:49], v[58:59] op_sel_hi:[1,0]
	v_pk_mul_f32 v[48:49], v[50:51], v[58:59] op_sel_hi:[1,0]
	global_store_dwordx2 v[34:35], v[12:13], off
	v_pk_mul_f32 v[12:13], v[26:27], v[48:49]
	v_pk_mul_f32 v[14:15], v[24:25], v[14:15]
	v_bfe_u32 v26, v12, 16, 1
	v_bfe_u32 v27, v13, 16, 1
	v_add3_u32 v12, v12, v26, s33
	v_add3_u32 v13, v13, v27, s33
	v_lshrrev_b32_e32 v24, 16, v12
	v_cvt_pk_bf16_f32 v12, v14, v15
	v_and_or_b32 v13, v13, s37, v24
	global_store_dwordx2 v[38:39], v[12:13], off
	global_load_dwordx4 v[12:15], v[30:31], off offset:1024
	v_pk_mul_f32 v[8:9], v[8:9], v[56:57] op_sel_hi:[1,0]
	v_pk_mul_f32 v[10:11], v[10:11], v[56:57] op_sel_hi:[1,0]
	v_pk_mul_f32 v[24:25], v[52:53], v[58:59] op_sel_hi:[1,0]
	v_pk_mul_f32 v[26:27], v[54:55], v[58:59] op_sel_hi:[1,0]
	v_pk_mul_f32 v[4:5], v[4:5], v[56:57] op_sel_hi:[1,0]
	v_pk_mul_f32 v[6:7], v[6:7], v[56:57] op_sel_hi:[1,0]
	v_pk_mul_f32 v[0:1], v[0:1], v[56:57] op_sel_hi:[1,0]
	v_pk_mul_f32 v[2:3], v[2:3], v[56:57] op_sel_hi:[1,0]
	s_waitcnt vmcnt(0)
	v_pk_mul_f32 v[10:11], v[14:15], v[10:11]
	v_pk_mul_f32 v[8:9], v[12:13], v[8:9]
	v_pk_mul_f32 v[14:15], v[14:15], v[26:27]
	v_pk_mul_f32 v[12:13], v[12:13], v[24:25]
	v_cvt_pk_bf16_f32 v8, v8, v9
	v_cvt_pk_bf16_f32 v9, v10, v11
	v_cvt_pk_bf16_f32 v10, v12, v13
	v_cvt_pk_bf16_f32 v11, v14, v15
	global_store_dwordx2 v[34:35], v[8:9], off offset:512
	global_store_dwordx2 v[38:39], v[10:11], off offset:512
	global_load_dwordx4 v[8:11], v[30:31], off offset:2048
	v_pk_mul_f32 v[12:13], v[20:21], v[58:59] op_sel_hi:[1,0]
	v_pk_mul_f32 v[14:15], v[22:23], v[58:59] op_sel_hi:[1,0]
	s_waitcnt vmcnt(0)
	v_pk_mul_f32 v[6:7], v[6:7], v[10:11]
	v_pk_mul_f32 v[4:5], v[4:5], v[8:9]
	v_pk_mul_f32 v[10:11], v[10:11], v[14:15]
	v_pk_mul_f32 v[8:9], v[8:9], v[12:13]
	v_cvt_pk_bf16_f32 v4, v4, v5
	v_cvt_pk_bf16_f32 v5, v6, v7
	v_cvt_pk_bf16_f32 v6, v8, v9
	v_cvt_pk_bf16_f32 v7, v10, v11
	global_store_dwordx2 v[34:35], v[4:5], off offset:1024
	global_store_dwordx2 v[38:39], v[6:7], off offset:1024
	global_load_dwordx4 v[4:7], v[30:31], off offset:3072
	v_pk_mul_f32 v[8:9], v[16:17], v[58:59] op_sel_hi:[1,0]
	v_pk_mul_f32 v[10:11], v[18:19], v[58:59] op_sel_hi:[1,0]
	s_waitcnt vmcnt(0)
	v_pk_mul_f32 v[2:3], v[2:3], v[6:7]
	v_pk_mul_f32 v[0:1], v[0:1], v[4:5]
	v_pk_mul_f32 v[6:7], v[10:11], v[6:7]
	v_pk_mul_f32 v[4:5], v[8:9], v[4:5]
	v_cvt_pk_bf16_f32 v0, v0, v1
	v_cvt_pk_bf16_f32 v1, v2, v3
	v_cvt_pk_bf16_f32 v2, v4, v5
	v_cvt_pk_bf16_f32 v3, v6, v7
	global_store_dwordx2 v[34:35], v[0:1], off offset:1536
	global_store_dwordx2 v[38:39], v[2:3], off offset:1536
	v_lshl_add_u64 v[34:35], v[34:35], 0, s[34:35]
	s_cbranch_scc0 .LBB0_69

; __device__ __forceinline__ void rms_row2(const float* xrow0, const float* xrow1, const float* g, bf16* xo0, bf16* xo1, float* fo0, float* fo1, int lane) {
;     const f32x4* xr0 = (const f32x4*)xrow0 + lane; const f32x4* xr1 = (const f32x4*)xrow1 + lane; const f32x4* gr = (const f32x4*)g + lane;
;     f32x4 v0[4], v1[4]; float s0 = 0.f, s1 = 0.f;
; #pragma unroll
;     for (int j = 0; j < 4; ++j) { v0[j] = xr0[64 * j]; v1[j] = xr1[64 * j]; }
; #pragma unroll
;     for (int j = 0; j < 4; ++j) { s0 += (v0[j].x * v0[j].x + v0[j].y * v0[j].y) + (v0[j].z * v0[j].z + v0[j].w * v0[j].w); s1 += (v1[j].x * v1[j].x + v1[j].y * v1[j].y) + (v1[j].z * v1[j].z + v1[j].w * v1[j].w); }
;     const float r0 = 1.0f / sqrtf(wave_sum(s0, lane) * (1.f / DM) + EPS), r1 = 1.0f / sqrtf(wave_sum(s1, lane) * (1.f / DM) + EPS);
; #pragma unroll
;     for (int j = 0; j < 4; ++j) { const f32x4 gg = gr[64 * j]; const f32x4 y0 = v0[j] * r0 * gg, y1 = v1[j] * r1 * gg;
.LBB0_276:
	s_add_i32 s0, s31, s6
	s_cmp_lt_i32 s0, 0x8000
	s_cselect_b32 s0, s0, s6
	s_ashr_i32 s1, s0, 31
	s_lshl_b64 s[4:5], s[0:1], 12
	v_lshl_add_u64 v[0:1], v[32:33], 0, s[4:5]
	global_load_dwordx4 v[28:31], v[40:41], off
	global_load_dwordx4 v[24:27], v[0:1], off
	global_load_dwordx4 v[20:23], v[40:41], off offset:1024
	global_load_dwordx4 v[16:19], v[0:1], off offset:1024
	global_load_dwordx4 v[12:15], v[40:41], off offset:2048
	global_load_dwordx4 v[8:11], v[0:1], off offset:2048
	global_load_dwordx4 v[4:7], v[40:41], off offset:3072
	s_nop 0
	global_load_dwordx4 v[0:3], v[0:1], off offset:3072
	s_lshl_b64 s[0:1], s[0:1], 11
	s_add_i32 s6, s6, s8
	v_lshl_add_u64 v[40:41], v[40:41], 0, s[14:15]
	s_cmpk_gt_i32 s6, 0x7fff
	s_waitcnt vmcnt(7)
	v_pk_mul_f32 v[50:51], v[30:31], v[30:31]
	v_pk_mul_f32 v[52:53], v[28:29], v[28:29]
	s_waitcnt vmcnt(1)
	v_mul_f32_e32 v42, v4, v4
	v_pk_mov_b32 v[54:55], v[52:53], v[50:51] op_sel:[1,0]
	v_mov_b32_e32 v53, v51
	v_pk_add_f32 v[50:51], v[54:55], v[52:53]
	v_pk_mul_f32 v[52:53], v[26:27], v[26:27]
	v_pk_mul_f32 v[54:55], v[24:25], v[24:25]
	v_mul_f32_e32 v44, v5, v5
	v_pk_mov_b32 v[56:57], v[54:55], v[52:53] op_sel:[1,0]
	v_mov_b32_e32 v55, v53
	v_pk_add_f32 v[52:53], v[56:57], v[54:55]
	v_pk_mul_f32 v[54:55], v[22:23], v[22:23]
	v_pk_mul_f32 v[56:57], v[20:21], v[20:21]
	v_pk_add_f32 v[50:51], v[50:51], v[50:51] op_sel:[0,1] op_sel_hi:[1,0]
	v_pk_mov_b32 v[58:59], v[56:57], v[54:55] op_sel:[1,0]
	v_mov_b32_e32 v57, v55
	v_pk_add_f32 v[54:55], v[58:59], v[56:57]
	v_pk_mul_f32 v[56:57], v[18:19], v[18:19]
	v_pk_mul_f32 v[58:59], v[16:17], v[16:17]
	v_pk_add_f32 v[54:55], v[54:55], v[54:55] op_sel:[0,1] op_sel_hi:[1,0]
	v_pk_mov_b32 v[60:61], v[58:59], v[56:57] op_sel:[1,0]
	v_mov_b32_e32 v59, v57
	v_mov_b32_e32 v51, v42
	v_mov_b32_e32 v55, v44
	v_mul_f32_e32 v42, v13, v13
	v_pk_add_f32 v[56:57], v[60:61], v[58:59]
	v_mul_f32_e32 v58, v6, v6
	v_pk_add_f32 v[50:51], v[50:51], v[54:55]
	v_pk_fma_f32 v[54:55], v[12:13], v[12:13], v[42:43] op_sel_hi:[1,1,0]
	v_mul_f32_e32 v42, v15, v15
	v_mul_f32_e32 v60, v7, v7
	v_mov_b32_e32 v55, v58
	v_pk_fma_f32 v[58:59], v[14:15], v[14:15], v[42:43] op_sel_hi:[1,1,0]
	s_waitcnt vmcnt(0)
	v_mul_f32_e32 v42, v0, v0
	v_mov_b32_e32 v59, v60
	v_pk_add_f32 v[54:55], v[54:55], v[58:59]
	v_mul_f32_e32 v58, v3, v3
	v_pk_add_f32 v[50:51], v[50:51], v[54:55]
	v_mul_f32_e32 v54, v1, v1
	v_add_f32_e32 v44, v50, v51
	v_pk_add_f32 v[50:51], v[52:53], v[52:53] op_sel:[0,1] op_sel_hi:[1,0]
	v_pk_add_f32 v[52:53], v[56:57], v[56:57] op_sel:[0,1] op_sel_hi:[1,0]
	v_mov_b32_e32 v51, v42
	v_mov_b32_e32 v53, v54
	v_mul_f32_e32 v42, v9, v9
	v_mul_f32_e32 v55, v2, v2
	v_pk_add_f32 v[50:51], v[50:51], v[52:53]
	v_pk_fma_f32 v[52:53], v[8:9], v[8:9], v[42:43] op_sel_hi:[1,1,0]
	v_mul_f32_e32 v42, v11, v11
	v_mov_b32_e32 v53, v55
	v_pk_fma_f32 v[54:55], v[10:11], v[10:11], v[42:43] op_sel_hi:[1,1,0]
	ds_bpermute_b32 v42, v43, v44
	v_mov_b32_e32 v55, v58
	v_pk_add_f32 v[52:53], v[52:53], v[54:55]
	s_waitcnt lgkmcnt(0)
	v_add_f32_e32 v42, v44, v42
	ds_bpermute_b32 v44, v45, v42
	v_pk_add_f32 v[50:51], v[50:51], v[52:53]
	s_waitcnt lgkmcnt(0)
	v_add_f32_e32 v42, v42, v44
	ds_bpermute_b32 v44, v46, v42
	v_add_f32_e32 v50, v50, v51
	s_waitcnt lgkmcnt(0)
	v_add_f32_e32 v42, v42, v44
	ds_bpermute_b32 v44, v47, v42
	s_waitcnt lgkmcnt(0)
	v_add_f32_e32 v42, v42, v44
	ds_bpermute_b32 v44, v48, v42
	s_waitcnt lgkmcnt(0)
	v_add_f32_e32 v42, v42, v44
	ds_bpermute_b32 v44, v49, v42
	s_waitcnt lgkmcnt(0)
	v_add_f32_e32 v42, v42, v44
	v_fmamk_f32 v42, v42, 0x3a800000, v240
	v_cmp_gt_f32_e32 vcc, s7, v42
	v_mul_f32_e32 v44, 0x4f800000, v42
	s_nop 0
	v_cndmask_b32_e32 v42, v42, v44, vcc
	v_sqrt_f32_e32 v44, v42
	s_nop 0
	v_add_u32_e32 v51, -1, v44
	v_fma_f32 v52, -v51, v44, v42
	v_cmp_ge_f32_e64 s[4:5], 0, v52
	v_add_u32_e32 v52, 1, v44
	s_nop 0
	v_cndmask_b32_e64 v51, v44, v51, s[4:5]
	v_fma_f32 v44, -v52, v44, v42
	v_cmp_lt_f32_e64 s[4:5], 0, v44
	s_nop 1
	v_cndmask_b32_e64 v44, v51, v52, s[4:5]
	v_mul_f32_e32 v51, 0x37800000, v44
	v_cndmask_b32_e32 v44, v44, v51, vcc
	v_cmp_class_f32_e32 vcc, v42, v244
	s_nop 1
	v_cndmask_b32_e32 v42, v44, v42, vcc
	v_div_scale_f32 v44, s[4:5], v42, v42, 1.0
	v_rcp_f32_e32 v51, v44
	s_nop 0
	v_fma_f32 v52, -v44, v51, 1.0
	v_fmac_f32_e32 v51, v52, v51
	v_div_scale_f32 v52, vcc, 1.0, v42, 1.0
	v_mul_f32_e32 v53, v52, v51
	v_fma_f32 v54, -v44, v53, v52
	v_fmac_f32_e32 v53, v54, v51
	v_fma_f32 v44, -v44, v53, v52
	v_div_fmas_f32 v44, v44, v51, v53
	v_div_fixup_f32 v42, v44, v42, 1.0
	ds_bpermute_b32 v44, v43, v50
	v_pk_mul_f32 v[28:29], v[28:29], v[42:43] op_sel_hi:[1,0]
	v_pk_mul_f32 v[30:31], v[30:31], v[42:43] op_sel_hi:[1,0]
	v_pk_mul_f32 v[20:21], v[20:21], v[42:43] op_sel_hi:[1,0]
	v_pk_mul_f32 v[22:23], v[22:23], v[42:43] op_sel_hi:[1,0]
	s_waitcnt lgkmcnt(0)
	v_add_f32_e32 v44, v50, v44
	ds_bpermute_b32 v50, v45, v44
	v_pk_mul_f32 v[12:13], v[12:13], v[42:43] op_sel_hi:[1,0]
	v_pk_mul_f32 v[14:15], v[14:15], v[42:43] op_sel_hi:[1,0]
	v_pk_mul_f32 v[4:5], v[4:5], v[42:43] op_sel_hi:[1,0]
	v_pk_mul_f32 v[6:7], v[6:7], v[42:43] op_sel_hi:[1,0]
	s_waitcnt lgkmcnt(0)
; __device__ __forceinline__ unsigned pk2(float lo, float hi) { return f2bf(lo) | (f2bf(hi) << 16); }
; __device__ __forceinline__ void rms_row2(const float* xrow0, const float* xrow1, const float* g, bf16* xo0, bf16* xo1, float* fo0, float* fo1, int lane) {
;     ...
;     const float r0 = 1.0f / sqrtf(wave_sum(s0, lane) * (1.f / DM) + EPS), r1 = 1.0f / sqrtf(wave_sum(s1, lane) * (1.f / DM) + EPS);
; #pragma unroll
;     for (int j = 0; j < 4; ++j) { const f32x4 gg = gr[64 * j]; const f32x4 y0 = v0[j] * r0 * gg, y1 = v1[j] * r1 * gg;
;         if (xo0) { ((unsigned long long*)xo0)[lane + 64 * j] = (unsigned long long)pk2(y0.x, y0.y) | ((unsigned long long)pk2(y0.z, y0.w) << 32);
;                    ((unsigned long long*)xo1)[lane + 64 * j] = (unsigned long long)pk2(y1.x, y1.y) | ((unsigned long long)pk2(y1.z, y1.w) << 32); }
;         else { ((f32x4*)fo0)[lane + 64 * j] = y0; ((f32x4*)fo1)[lane + 64 * j] = y1; } }
	v_add_f32_e32 v44, v44, v50
	ds_bpermute_b32 v50, v46, v44
	s_waitcnt lgkmcnt(0)
	v_add_f32_e32 v44, v44, v50
	ds_bpermute_b32 v50, v47, v44
	s_waitcnt lgkmcnt(0)
	v_add_f32_e32 v44, v44, v50
	ds_bpermute_b32 v50, v48, v44
	s_waitcnt lgkmcnt(0)
	v_add_f32_e32 v44, v44, v50
	ds_bpermute_b32 v50, v49, v44
	s_waitcnt lgkmcnt(0)
	v_add_f32_e32 v44, v44, v50
	v_fmamk_f32 v44, v44, 0x3a800000, v240
	v_cmp_gt_f32_e32 vcc, s7, v44
	v_mul_f32_e32 v50, 0x4f800000, v44
	s_nop 0
	v_cndmask_b32_e32 v44, v44, v50, vcc
	v_sqrt_f32_e32 v50, v44
	s_nop 0
	v_add_u32_e32 v51, -1, v50
	v_fma_f32 v52, -v51, v50, v44
	v_cmp_ge_f32_e64 s[4:5], 0, v52
	v_add_u32_e32 v52, 1, v50
	s_nop 0
	v_cndmask_b32_e64 v51, v50, v51, s[4:5]
	v_fma_f32 v50, -v52, v50, v44
	v_cmp_lt_f32_e64 s[4:5], 0, v50
	s_nop 1
	v_cndmask_b32_e64 v50, v51, v52, s[4:5]
	v_mul_f32_e32 v51, 0x37800000, v50
	v_cndmask_b32_e32 v50, v50, v51, vcc
	v_cmp_class_f32_e32 vcc, v44, v244
	s_nop 1
	v_cndmask_b32_e32 v44, v50, v44, vcc
	v_div_scale_f32 v50, s[4:5], v44, v44, 1.0
	v_rcp_f32_e32 v51, v50
	s_nop 0
	v_fma_f32 v52, -v50, v51, 1.0
	v_fmac_f32_e32 v51, v52, v51
	v_div_scale_f32 v52, vcc, 1.0, v44, 1.0
	v_mul_f32_e32 v53, v52, v51
	v_fma_f32 v54, -v50, v53, v52
	v_fmac_f32_e32 v53, v54, v51
	v_fma_f32 v50, -v50, v53, v52
	v_div_fmas_f32 v50, v50, v51, v53
	v_div_fixup_f32 v44, v50, v44, 1.0
	global_load_dwordx4 v[50:53], v[34:35], off
	v_pk_mul_f32 v[26:27], v[26:27], v[44:45] op_sel_hi:[1,0]
	v_pk_mul_f32 v[24:25], v[24:25], v[44:45] op_sel_hi:[1,0]
	v_pk_mul_f32 v[16:17], v[16:17], v[44:45] op_sel_hi:[1,0]
	v_pk_mul_f32 v[18:19], v[18:19], v[44:45] op_sel_hi:[1,0]
	v_pk_mul_f32 v[8:9], v[8:9], v[44:45] op_sel_hi:[1,0]
	v_pk_mul_f32 v[10:11], v[10:11], v[44:45] op_sel_hi:[1,0]
	v_pk_mul_f32 v[0:1], v[0:1], v[44:45] op_sel_hi:[1,0]
	v_pk_mul_f32 v[2:3], v[2:3], v[44:45] op_sel_hi:[1,0]
	s_waitcnt vmcnt(0)
	v_pk_mul_f32 v[28:29], v[50:51], v[28:29]
	v_pk_mul_f32 v[30:31], v[52:53], v[30:31]
	v_pk_mul_f32 v[52:53], v[52:53], v[26:27]
	v_bfe_u32 v26, v28, 16, 1
	v_add3_u32 v26, v28, v26, s33
	v_bfe_u32 v27, v29, 16, 1
	v_lshrrev_b32_e32 v26, 16, v26
	v_add3_u32 v27, v29, v27, s33
	v_and_or_b32 v26, v27, s37, v26
	v_bfe_u32 v27, v30, 16, 1
	v_add3_u32 v27, v30, v27, s33
	v_bfe_u32 v28, v31, 16, 1
	v_lshrrev_b32_e32 v27, 16, v27
	v_add3_u32 v28, v31, v28, s33
	v_pk_mul_f32 v[24:25], v[50:51], v[24:25]
	v_and_or_b32 v27, v28, s37, v27
	global_store_dwordx2 v[38:39], v[26:27], off
	v_bfe_u32 v26, v24, 16, 1
	v_add3_u32 v24, v24, v26, s33
	v_bfe_u32 v26, v25, 16, 1
	v_lshrrev_b32_e32 v24, 16, v24
	v_add3_u32 v25, v25, v26, s33
	v_and_or_b32 v26, v25, s37, v24
	v_cvt_pk_bf16_f32 v27, v52, v53
	v_lshl_add_u64 v[24:25], v[36:37], 0, s[0:1]
	global_store_dwordx2 v[24:25], v[26:27], off
	global_load_dwordx4 v[26:29], v[34:35], off offset:1024
	s_waitcnt vmcnt(0)
	v_pk_mul_f32 v[20:21], v[26:27], v[20:21]
	v_pk_mul_f32 v[16:17], v[26:27], v[16:17]
	v_pk_mul_f32 v[22:23], v[28:29], v[22:23]
	v_cvt_pk_bf16_f32 v20, v20, v21
	v_bfe_u32 v21, v22, 16, 1
	v_add3_u32 v21, v22, v21, s33
	v_bfe_u32 v22, v23, 16, 1
	v_lshrrev_b32_e32 v21, 16, v21
	v_add3_u32 v22, v23, v22, s33
	v_and_or_b32 v21, v22, s37, v21
	global_store_dwordx2 v[38:39], v[20:21], off offset:512
	v_pk_mul_f32 v[18:19], v[28:29], v[18:19]
	v_cvt_pk_bf16_f32 v16, v16, v17
	v_bfe_u32 v17, v18, 16, 1
	v_add3_u32 v17, v18, v17, s33
	v_bfe_u32 v18, v19, 16, 1
	v_lshrrev_b32_e32 v17, 16, v17
	v_add3_u32 v18, v19, v18, s33
	v_and_or_b32 v17, v18, s37, v17
	global_store_dwordx2 v[24:25], v[16:17], off offset:512
	global_load_dwordx4 v[16:19], v[34:35], off offset:2048
	s_waitcnt vmcnt(0)
	v_pk_mul_f32 v[12:13], v[12:13], v[16:17]
	v_pk_mul_f32 v[8:9], v[16:17], v[8:9]
	v_pk_mul_f32 v[14:15], v[14:15], v[18:19]
	v_cvt_pk_bf16_f32 v12, v12, v13
	v_bfe_u32 v13, v14, 16, 1
	v_add3_u32 v13, v14, v13, s33
	v_bfe_u32 v14, v15, 16, 1
	v_lshrrev_b32_e32 v13, 16, v13
	v_add3_u32 v14, v15, v14, s33
	v_and_or_b32 v13, v14, s37, v13
	global_store_dwordx2 v[38:39], v[12:13], off offset:1024
	v_pk_mul_f32 v[10:11], v[18:19], v[10:11]
	v_cvt_pk_bf16_f32 v8, v8, v9
	v_bfe_u32 v9, v10, 16, 1
	v_add3_u32 v9, v10, v9, s33
	v_bfe_u32 v10, v11, 16, 1
	v_lshrrev_b32_e32 v9, 16, v9
	v_add3_u32 v10, v11, v10, s33
	v_and_or_b32 v9, v10, s37, v9
	global_store_dwordx2 v[24:25], v[8:9], off offset:1024
	global_load_dwordx4 v[8:11], v[34:35], off offset:3072
	s_waitcnt vmcnt(0)
	v_pk_mul_f32 v[4:5], v[4:5], v[8:9]
	v_pk_mul_f32 v[0:1], v[0:1], v[8:9]
	v_pk_mul_f32 v[6:7], v[6:7], v[10:11]
	v_cvt_pk_bf16_f32 v4, v4, v5
	v_bfe_u32 v5, v6, 16, 1
	v_add3_u32 v5, v6, v5, s33
	v_bfe_u32 v6, v7, 16, 1
	v_lshrrev_b32_e32 v5, 16, v5
	v_add3_u32 v6, v7, v6, s33
	v_and_or_b32 v5, v6, s37, v5
	global_store_dwordx2 v[38:39], v[4:5], off offset:1536
	v_pk_mul_f32 v[2:3], v[2:3], v[10:11]
	v_cvt_pk_bf16_f32 v0, v0, v1
	v_bfe_u32 v1, v2, 16, 1
	v_add3_u32 v1, v2, v1, s33
	v_bfe_u32 v2, v3, 16, 1
	v_lshrrev_b32_e32 v1, 16, v1
	v_add3_u32 v2, v3, v2, s33
	v_and_or_b32 v1, v2, s37, v1
	v_lshl_add_u64 v[38:39], v[38:39], 0, s[34:35]
	global_store_dwordx2 v[24:25], v[0:1], off offset:1536
	s_cbranch_scc0 .LBB0_276
